# fetch: DONE counters bumped right after each stage (slot-0 chunk behind its batch, slot-1 chunk after its stage)
# speedup vs baseline: 1.0040x; 1.0040x over previous
.Lfetch_nop0:
	s_mov_b32 s99, 0
	s_mov_b64 s[100:101], exec
	v_mbcnt_lo_u32_b32 v231, s100, 0
	v_mbcnt_hi_u32_b32 v231, s101, v231
	v_cmp_eq_u32_e32 vcc, 0, v231
	s_and_saveexec_b64 s[100:101], vcc
	v_mov_b32_e32 v231, 64
	global_atomic_add v1, v231, s[40:41]
	s_or_b64 exec, exec, s[100:101]
	s_add_i32 s98, s98, 1
	s_mov_b32 s99, 1

.Lfetch_nopv:
	v_lshlrev_b32_e32 v220, 16, v184
	v_and_b32_e32 v221, 0xffff0000, v184
	v_lshlrev_b32_e32 v184, 16, v185
	v_and_b32_e32 v185, 0xffff0000, v185
	v_lshlrev_b32_e32 v3, 16, v182
	v_and_b32_e32 v182, 0xffff0000, v182
	v_lshlrev_b32_e32 v195, 16, v183
	v_and_b32_e32 v222, 0xffff0000, v183
	s_mul_hi_u32 s6, s87, 0xaaaaaaab
	v_sub_f32_e32 v183, v182, v221
	v_sub_f32_e32 v182, v3, v220
	v_sub_f32_e32 v223, v222, v185
	v_sub_f32_e32 v222, v195, v184
	s_lshr_b32 s6, s6, 3
	v_pk_fma_f32 v[184:185], v[54:55], v[222:223], v[184:185]
	v_pk_fma_f32 v[182:183], v[52:53], v[182:183], v[220:221]
	s_mul_i32 s6, s6, 12
	v_cvt_pk_bf16_f32 v182, v182, v183
	v_cvt_pk_bf16_f32 v183, v184, v185
	s_sub_i32 s6, s87, s6
	s_mul_i32 s7, s6, 0x2b00
	s_add_i32 s7, s7, 0
	v_add_u32_e32 v3, s7, v196
	ds_write_b128 v3, v[116:119]
	ds_write_b128 v3, v[136:139] offset:1024
	ds_write_b128 v3, v[140:143] offset:2048
	ds_write_b128 v3, v[112:115] offset:3072
	ds_write_b128 v3, v[104:107] offset:4096
	ds_write_b128 v3, v[132:135] offset:5120
	ds_write_b128 v3, v[108:111] offset:6144
	ds_write_b128 v3, v[144:147] offset:7168
	ds_write_b128 v3, v[120:123] offset:8192
	ds_write_b128 v3, v[124:127] offset:9216
	v_mfma_f32_16x16x16_bf16 v[104:107], v[182:183], v[150:151], 0
	v_mov_b64_e32 v[182:183], v[240:241]
	v_mov_b64_e32 v[184:185], v[242:243]
	s_lshl_b32 s6, s6, 2
	v_add_u32_e32 v3, s7, v202
	s_add_i32 s6, s6, 0
	ds_write_b128 v3, v[128:131] offset:10752
	v_add_u32_e32 v3, s7, v203
	s_nop 2
	v_cvt_pk_bf16_f32 v104, v104, v105
	v_cvt_pk_bf16_f32 v105, v106, v107
	s_add_i32 s7, s72, 5
	s_add_i32 s6, s6, 0x27400
	ds_write_b64 v3, v[104:105] offset:10240
	v_mov_b32_e32 v3, s6
	v_mov_b32_e32 v104, s7
	s_mov_b64 s[6:7], exec
	s_waitcnt lgkmcnt(0)
	ds_write_b32 v3, v104
	v_mbcnt_lo_u32_b32 v3, s6, 0
	v_mbcnt_hi_u32_b32 v3, s7, v3
	v_cmp_eq_u32_e32 vcc, 0, v3
	s_and_saveexec_b64 s[16:17], vcc
	s_cbranch_execz .LBB0_759
	s_bcnt1_i32_b64 s6, s[6:7]
	v_mov_b32_e32 v3, s6
	global_atomic_add v1, v3, s[40:41] offset:16
	s_add_i32 s99, s99, 1
